# scan gate math: bias add + log2e scaling folded into one fmamk; av exponent constant premultiplied
# speedup vs baseline: 1.0221x; 1.0009x over previous
; __device__ __forceinline__ float bf2f(unsigned b) { return __uint_as_float(b << 16); }
; __device__ __forceinline__ float fexp(float x) { return __builtin_amdgcn_exp2f(x * 1.4426950408889634f); }
; __device__ __forceinline__ float fsqrt(float x) { return __builtin_amdgcn_sqrtf(x); }
; __device__ __forceinline__ float sigmoidf_(float x) { return frcp(1.0f + fexp(-x)); }
; __device__ __forceinline__ int ukey(int tk) { return ((tk >> 4) << 2) | (tk & 3); }
; __device__ __forceinline__ void lru_scan_phase(const Params& p, int slot, const bf16_t* upre, bf16_t* hf, bf16_t* hb, char* smem, const bf16_t* gateA, bf16_t* gate_out) {
;     ...
;     const float gbr = gb[(d * 2 + 0) * DRNN + ch], gbi = gb[(d * 2 + 1) * DRNN + ch];
;     const float sp8 = 8.0f * log1pf(expf(-lam[d * DRNN + ch]));
;     ...
;             const int tkr = (fr >> 2) * 16 + mt * 4 + (fr & 3);
; #pragma unroll
;             for (int ks = 0; ks < 4; ++ks) {
;                 bf16x8 af = *reinterpret_cast<const bf16x8*>(smem + tkr * 256 + (((ks * 4 + fq) ^ ukey(tkr)) * 16));
;                 acc[0][mt] = mfma16(af, bfr[0][ks], acc[0][mt]);
;                 acc[1][mt] = mfma16(af, bfr[1][ks], acc[1][mt]);
;             }
;         }
;         float P = 1.f, H = 0.f;
; #pragma unroll
;         for (int ii = 0; ii < 16; ++ii) {
;             const int idxa = ii, idxd = 15 - ii;
;             (void)idxa; (void)idxd;
;         }
;         if (d == 0) {
; #pragma unroll
;             for (int ii = 0; ii < 16; ++ii) {
;                 const int mt = ii >> 2, j = ii & 3, tk = fq * 16 + ii;
;                 const float uval = bf2f(*reinterpret_cast<const bf16_t*>(smem + tk * 256 + (((chw >> 3) ^ ukey(tk)) * 16) + (chw & 7) * 2));
;                 const float r = sigmoidf_(acc[0][mt][j] + gbr), iv = sigmoidf_(acc[1][mt][j] + gbi);
;                 const float av = fexp(-sp8 * r);
;                 const float bv = fsqrt(fmaxf(1.f - av * av, 0.f)) * iv * uval;
;                 acc[0][mt][j] = av; acc[1][mt][j] = bv;
;                 H = av * H + bv; P *= av;
;             }
;         } else {
; #pragma unroll
;     ...
;                 const int mt = ii >> 2, j = ii & 3, tk = fq * 16 + ii;
;                 const float uval = bf2f(*reinterpret_cast<const bf16_t*>(smem + tk * 256 + (((chw >> 3) ^ ukey(tk)) * 16) + (chw & 7) * 2));
.LBB0_945:
	s_or_b64 exec, exec, s[10:11]
	s_waitcnt vmcnt(0)
	v_mul_f32_e32 v1, 0xbfb8aa3b, v109
	v_rndne_f32_e32 v2, v1
	s_mov_b32 s0, 0xbfb8aa3b
	v_sub_f32_e32 v3, v1, v2
	v_fma_f32 v1, v109, s0, -v1
	v_fmac_f32_e32 v1, 0xb2a5705f, v109
	v_add_f32_e32 v1, v3, v1
	v_cvt_i32_f32_e32 v2, v2
	v_exp_f32_e32 v1, v1
	s_mov_b32 s0, 0x42ce8ed0
	v_cmp_nlt_f32_e32 vcc, s0, v109
	s_mov_b32 s0, 0xc2b17218
	v_ldexp_f32 v1, v1, v2
	v_cndmask_b32_e32 v1, 0, v1, vcc
	v_cmp_ngt_f32_e32 vcc, s0, v109
	s_mov_b32 s0, 0x3f2aaaab
	s_and_b64 s[4:5], s[8:9], exec
	v_cndmask_b32_e32 v1, v190, v1, vcc
	v_add_f32_e32 v109, 1.0, v1
	v_add_f32_e32 v2, -1.0, v109
	v_sub_f32_e32 v3, v2, v109
	v_add_f32_e32 v3, 1.0, v3
	v_sub_f32_e32 v2, v1, v2
	v_add_f32_e32 v111, v2, v3
	v_frexp_mant_f32_e32 v118, v109
	v_cvt_f64_f32_e32 v[2:3], v109
	v_frexp_exp_i32_f64_e32 v2, v[2:3]
	v_cmp_gt_f32_e32 vcc, s0, v118
	s_mov_b32 s0, 0x3f317218
	s_cselect_b32 s1, s52, s56
	v_subbrev_co_u32_e32 v2, vcc, 0, v2, vcc
	v_sub_u32_e32 v3, 0, v2
	v_ldexp_f32 v109, v109, v3
	v_ldexp_f32 v3, v111, v3
	v_add_f32_e32 v111, -1.0, v109
	v_add_f32_e32 v120, 1.0, v109
	v_add_f32_e32 v118, 1.0, v111
	v_add_f32_e32 v121, -1.0, v120
	v_sub_f32_e32 v118, v109, v118
	v_sub_f32_e32 v109, v109, v121
	v_add_f32_e32 v118, v3, v118
	v_add_f32_e32 v3, v3, v109
	v_add_f32_e32 v109, v120, v3
	v_rcp_f32_e32 v121, v109
	v_add_f32_e32 v119, v111, v118
	v_sub_f32_e32 v111, v111, v119
	v_add_f32_e32 v111, v118, v111
	v_sub_f32_e32 v118, v120, v109
	v_add_f32_e32 v3, v3, v118
	v_mul_f32_e32 v118, v119, v121
	v_mul_f32_e32 v120, v109, v118
	v_fma_f32 v122, v118, v109, -v120
	v_fmac_f32_e32 v122, v118, v3
	v_add_f32_e32 v123, v120, v122
	v_sub_f32_e32 v124, v119, v123
	v_sub_f32_e32 v119, v119, v124
	v_sub_f32_e32 v120, v123, v120
	v_sub_f32_e32 v119, v119, v123
	v_add_f32_e32 v111, v111, v119
	v_sub_f32_e32 v119, v120, v122
	v_add_f32_e32 v111, v119, v111
	v_add_f32_e32 v119, v124, v111
	v_mul_f32_e32 v120, v121, v119
	v_mul_f32_e32 v122, v109, v120
	v_fma_f32 v109, v120, v109, -v122
	v_fmac_f32_e32 v109, v120, v3
	v_sub_f32_e32 v3, v124, v119
	v_add_f32_e32 v3, v111, v3
	v_add_f32_e32 v111, v122, v109
	v_sub_f32_e32 v123, v119, v111
	v_sub_f32_e32 v119, v119, v123
	v_sub_f32_e32 v122, v111, v122
	v_sub_f32_e32 v111, v119, v111
	v_add_f32_e32 v3, v3, v111
	v_sub_f32_e32 v109, v122, v109
	v_cvt_f32_i32_e32 v2, v2
	v_add_f32_e32 v3, v109, v3
	v_add_f32_e32 v109, v118, v120
	v_add_f32_e32 v3, v123, v3
	v_sub_f32_e32 v111, v109, v118
	v_mul_f32_e32 v3, v121, v3
	v_sub_f32_e32 v111, v120, v111
	v_add_f32_e32 v3, v111, v3
	v_mul_f32_e32 v120, 0x3f317218, v2
	v_add_f32_e32 v111, v109, v3
	v_fma_f32 v121, v2, s0, -v120
	v_mul_f32_e32 v118, v111, v111
	v_fmac_f32_e32 v121, 0xb102e308, v2
	v_sub_f32_e32 v2, v111, v109
	v_fmamk_f32 v119, v118, 0x3e9b6dac, v179
	v_sub_f32_e32 v2, v3, v2
	v_add_f32_e32 v3, v120, v121
	v_fmaak_f32 v119, v118, v119, 0x3f2aaada
	v_sub_f32_e32 v109, v3, v120
	v_ldexp_f32 v120, v111, 1
	v_mul_f32_e32 v111, v111, v118
	v_mul_f32_e32 v111, v111, v119
	v_add_f32_e32 v118, v120, v111
	v_sub_f32_e32 v119, v118, v120
	v_ldexp_f32 v2, v2, 1
	v_sub_f32_e32 v111, v111, v119
	v_add_f32_e32 v2, v2, v111
	v_add_f32_e32 v111, v118, v2
	v_sub_f32_e32 v118, v111, v118
	v_sub_f32_e32 v2, v2, v118
	v_add_f32_e32 v118, v3, v111
	v_sub_f32_e32 v119, v118, v3
	v_sub_f32_e32 v120, v118, v119
	v_sub_f32_e32 v109, v121, v109
	v_sub_f32_e32 v3, v3, v120
	v_sub_f32_e32 v111, v111, v119
	v_add_f32_e32 v3, v111, v3
	v_add_f32_e32 v111, v109, v2
	v_sub_f32_e32 v119, v111, v109
	v_sub_f32_e32 v120, v111, v119
	v_sub_f32_e32 v109, v109, v120
	v_sub_f32_e32 v2, v2, v119
	v_add_f32_e32 v3, v111, v3
	v_add_f32_e32 v2, v2, v109
	v_add_f32_e32 v109, v118, v3
	v_sub_f32_e32 v111, v109, v118
	v_sub_f32_e32 v3, v3, v111
	v_add_f32_e32 v2, v2, v3
	s_mov_b32 s0, 0x7f800000
	v_add_f32_e32 v2, v109, v2
	v_cmp_neq_f32_e32 vcc, s0, v1
	s_mov_b32 s0, 0x33800000
	v_ashrrev_i32_e32 v109, 31, v108
	v_cndmask_b32_e32 v2, v190, v2, vcc
	v_cmp_lt_f32_e64 vcc, |v1|, s0
	s_cselect_b32 s0, s53, s57
	v_mov_b32_e32 v3, s0
	v_cndmask_b32_e32 v1, v2, v1, vcc
	v_mov_b32_e32 v2, s1
	v_lshl_add_u64 v[118:119], v[108:109], 1, v[2:3]
	v_ashrrev_i32_e32 v2, 3, v114
	v_lshlrev_b32_e32 v108, 2, v193
	v_mul_f32_e32 v197, 0xc1000000, v1
	v_lshl_add_u32 v1, v193, 12, 0
	v_bitop3_b32 v125, v108, v2, 3 bitop3:0x36
	v_bitop3_b32 v126, v108, v2, 2 bitop3:0x36
	v_bitop3_b32 v127, v108, v2, 1 bitop3:0x36
	v_lshlrev_b32_e32 v128, 6, v193
	v_lshlrev_b32_e32 v129, 4, v2
	v_xor_b32_e32 v2, v2, v108
	v_cmp_lt_u32_e32 vcc, 1, v193
	v_readlane_b32 s0, v254, 27
	v_lshl_add_u32 v125, v125, 4, v1
	v_lshl_add_u32 v126, v126, 4, v1
	v_lshl_add_u32 v127, v127, 4, v1
	v_xad_u32 v128, v129, v128, v1
	v_lshl_add_u32 v1, v2, 4, v1
	v_cndmask_b32_e64 v2, 0, 1, vcc
	v_cmp_ge_u32_e32 vcc, s0, v193
	v_readlane_b32 s0, v252, 32
	v_mov_b32_e32 v111, v0
	v_cndmask_b32_e64 v108, 0, 1, vcc
	v_cndmask_b32_e64 v2, v108, v2, s[8:9]
	v_and_b32_e32 v2, 1, v2
	v_cmp_lt_u32_e32 vcc, s0, v193
	v_lshl_add_u64 v[120:121], s[48:49], 0, v[110:111]
	v_lshlrev_b32_e32 v3, 1, v112
	v_ashrrev_i32_e32 v110, 6, v112
	v_ashrrev_i32_e32 v114, 6, v115
	v_lshlrev_b32_e32 v123, 10, v112
	v_lshlrev_b32_e32 v112, 8, v112
	v_cmp_eq_u32_e64 s[44:45], 1, v2
	v_cndmask_b32_e64 v2, 0, 1, vcc
	v_cmp_gt_u32_e32 vcc, s0, v193
	v_and_b32_e32 v110, 0xffffffc, v110
	v_and_b32_e32 v114, 0xffffffc, v114
	v_bfe_u32 v115, v115, 4, 2
	v_and_b32_e32 v123, 0x3000, v123
	v_and_b32_e32 v112, 0x300, v112
	v_cndmask_b32_e64 v108, 0, 1, vcc
	v_and_or_b32 v122, v180, 64, v113
	v_bitop3_b32 v110, v110, v113, v193 bitop3:0x36
	v_bitop3_b32 v114, v114, v113, v115 bitop3:0x36
	v_xor_b32_e32 v115, v193, v113
	v_add3_u32 v112, 0, v123, v112
	v_bitop3_b32 v123, v193, v113, 4 bitop3:0x36
	v_bitop3_b32 v124, v193, v113, 8 bitop3:0x36
	v_bitop3_b32 v113, v193, v113, 12 bitop3:0x36
	v_cndmask_b32_e64 v2, v108, v2, s[8:9]
	v_and_b32_e32 v3, 14, v3
	v_lshl_add_u32 v109, v195, 8, 0
	v_lshlrev_b32_e32 v110, 4, v110
	v_lshl_add_u32 v111, v196, 8, 0
	v_lshlrev_b32_e32 v114, 4, v114
	v_lshlrev_b32_e32 v115, 4, v115
	v_lshlrev_b32_e32 v123, 4, v123
	v_lshlrev_b32_e32 v124, 4, v124
	v_lshlrev_b32_e32 v113, 4, v113
	v_lshlrev_b32_e32 v198, 2, v122
	v_and_b32_e32 v2, 1, v2
	s_mov_b32 s12, 0
	s_mov_b32 s5, -1
	v_or_b32_e32 v199, 64, v198
	v_or_b32_e32 v200, 0x80, v198
	v_or_b32_e32 v201, 0xc0, v198
	v_cmp_eq_u32_e64 s[46:47], 1, v2
	v_add_u32_e32 v202, v109, v110
	v_add_u32_e32 v203, v111, v114
	v_add_u32_e32 v204, v112, v115
	v_add_u32_e32 v205, v112, v123
	v_add_u32_e32 v207, v112, v124
	v_add_u32_e32 v208, v112, v113
	v_add_u32_e32 v209, v128, v3
	v_add_u32_e32 v210, v1, v3
	v_add_u32_e32 v211, v125, v3
	v_add_u32_e32 v212, v126, v3
	v_add_u32_e32 v213, v127, v3
	s_waitcnt vmcnt(0)
	v_mul_f32_e32 v246, 0xbfb8aa3b, v117
	v_mul_f32_e32 v247, 0xbfb8aa3b, v194
	v_mul_f32_e32 v248, 0x3fb8aa3b, v197
	s_branch .LBB0_947

; __device__ __forceinline__ float bf2f(unsigned b) { return __uint_as_float(b << 16); }
; __device__ __forceinline__ float sigmoidf_(float x) { return frcp(1.0f + fexp(-x)); }
; __device__ __forceinline__ int ukey(int tk) { return ((tk >> 4) << 2) | (tk & 3); }
; __device__ __forceinline__ void lru_scan_phase(const Params& p, int slot, const bf16_t* upre, bf16_t* hf, bf16_t* hb, char* smem, const bf16_t* gateA, bf16_t* gate_out) {
;     ...
;         for (int mt = 0; mt < 4; ++mt) {
;             const int tkr = (fr >> 2) * 16 + mt * 4 + (fr & 3);
; #pragma unroll
;             for (int ks = 0; ks < 4; ++ks) {
;                 bf16x8 af = *reinterpret_cast<const bf16x8*>(smem + tkr * 256 + (((ks * 4 + fq) ^ ukey(tkr)) * 16));
;                 acc[0][mt] = mfma16(af, bfr[0][ks], acc[0][mt]);
;                 acc[1][mt] = mfma16(af, bfr[1][ks], acc[1][mt]);
;             }
;         }
;         float P = 1.f, H = 0.f;
; #pragma unroll
;         for (int ii = 0; ii < 16; ++ii) {
;             const int idxa = ii, idxd = 15 - ii;
;             (void)idxa; (void)idxd;
;         }
;         if (d == 0) {
; #pragma unroll
;             for (int ii = 0; ii < 16; ++ii) {
;                 const int mt = ii >> 2, j = ii & 3, tk = fq * 16 + ii;
;                 const float uval = bf2f(*reinterpret_cast<const bf16_t*>(smem + tk * 256 + (((chw >> 3) ^ ukey(tk)) * 16) + (chw & 7) * 2));
;                 const float r = sigmoidf_(acc[0][mt][j] + gbr), iv = sigmoidf_(acc[1][mt][j] + gbi);
.LBB0_965:
	ds_read_b128 v[108:111], v204
	ds_read_b128 v[122:125], v205
	v_readlane_b32 s0, v252, 22
	v_readlane_b32 s1, v252, 23
	s_mov_b64 s[10:11], -1
	s_andn2_b64 vcc, exec, s[0:1]
	v_cndmask_b32_e64 v1, 0, 1, s[0:1]
	v_cmp_ne_u32_e64 s[48:49], 1, v1
	s_waitcnt lgkmcnt(1)
	v_mfma_f32_16x16x32_bf16 v[112:115], v[108:111], v[44:47], 0
	ds_read_b128 v[126:129], v208
	ds_read_b128 v[130:133], v205 offset:1024
	ds_read_b128 v[154:157], v205 offset:2048
	v_mfma_f32_16x16x32_bf16 v[108:111], v[108:111], v[60:63], 0
	s_waitcnt lgkmcnt(3)
	v_mfma_f32_16x16x32_bf16 v[112:115], v[122:125], v[48:51], v[112:115]
	v_mfma_f32_16x16x32_bf16 v[108:111], v[122:125], v[64:67], v[108:111]
	ds_read_b128 v[122:125], v207
	s_waitcnt lgkmcnt(0)
	v_mfma_f32_16x16x32_bf16 v[112:115], v[122:125], v[52:55], v[112:115]
	v_mfma_f32_16x16x32_bf16 v[122:125], v[122:125], v[68:71], v[108:111]
	v_mfma_f32_16x16x32_bf16 v[108:111], v[126:129], v[56:59], v[112:115]
	v_mfma_f32_16x16x32_bf16 v[112:115], v[126:129], v[72:75], v[122:125]
	s_nop 5
	ds_read_b128 v[122:125], v204 offset:1024
	s_waitcnt lgkmcnt(0)
	v_mfma_f32_16x16x32_bf16 v[126:129], v[122:125], v[44:47], 0
	v_fmamk_f32 v233, v111, 0xbfb8aa3b, v246
	v_fmamk_f32 v234, v115, 0xbfb8aa3b, v247
	v_fmamk_f32 v236, v110, 0xbfb8aa3b, v246
	v_mfma_f32_16x16x32_bf16 v[122:125], v[122:125], v[60:63], 0
	v_fmamk_f32 v235, v114, 0xbfb8aa3b, v247
	v_fmamk_f32 v238, v109, 0xbfb8aa3b, v246
	v_fmamk_f32 v237, v113, 0xbfb8aa3b, v247
	v_mfma_f32_16x16x32_bf16 v[126:129], v[130:133], v[48:51], v[126:129]
	v_fmamk_f32 v240, v108, 0xbfb8aa3b, v246
	v_fmamk_f32 v239, v112, 0xbfb8aa3b, v247
	v_mfma_f32_16x16x32_bf16 v[122:125], v[130:133], v[64:67], v[122:125]
	ds_read_b128 v[130:133], v207 offset:1024
	s_waitcnt lgkmcnt(0)
	v_mfma_f32_16x16x32_bf16 v[126:129], v[130:133], v[52:55], v[126:129]
	v_mfma_f32_16x16x32_bf16 v[122:125], v[130:133], v[68:71], v[122:125]
	ds_read_b128 v[130:133], v208 offset:1024
	s_waitcnt lgkmcnt(0)
	v_mfma_f32_16x16x32_bf16 v[158:161], v[130:133], v[56:59], v[126:129]
	v_mfma_f32_16x16x32_bf16 v[128:131], v[130:133], v[72:75], v[122:125]
	s_nop 6
	v_fmamk_f32 v226, v161, 0xbfb8aa3b, v246
	v_fmamk_f32 v227, v160, 0xbfb8aa3b, v246
	v_fmamk_f32 v230, v159, 0xbfb8aa3b, v246
	ds_read_b128 v[122:125], v204 offset:2048
	s_waitcnt lgkmcnt(0)
	v_mfma_f32_16x16x32_bf16 v[150:153], v[122:125], v[44:47], 0
	v_fmamk_f32 v225, v131, 0xbfb8aa3b, v247
	v_fmamk_f32 v228, v130, 0xbfb8aa3b, v247
	v_fmamk_f32 v229, v129, 0xbfb8aa3b, v247
	v_mfma_f32_16x16x32_bf16 v[122:125], v[122:125], v[60:63], 0
	v_fmamk_f32 v232, v158, 0xbfb8aa3b, v246
	v_fmamk_f32 v231, v128, 0xbfb8aa3b, v247
	v_mfma_f32_16x16x32_bf16 v[150:153], v[154:157], v[48:51], v[150:153]
	v_mfma_f32_16x16x32_bf16 v[122:125], v[154:157], v[64:67], v[122:125]
	ds_read_b128 v[154:157], v207 offset:2048
	s_waitcnt lgkmcnt(0)
	v_mfma_f32_16x16x32_bf16 v[150:153], v[154:157], v[52:55], v[150:153]
	v_mfma_f32_16x16x32_bf16 v[122:125], v[154:157], v[68:71], v[122:125]
	ds_read_b128 v[154:157], v208 offset:2048
	s_waitcnt lgkmcnt(0)
	v_mfma_f32_16x16x32_bf16 v[166:169], v[154:157], v[72:75], v[122:125]
	s_nop 4
	ds_read_b128 v[122:125], v204 offset:3072
	s_nop 1
	v_fmamk_f32 v222, v167, 0xbfb8aa3b, v247
	v_mfma_f32_16x16x32_bf16 v[162:165], v[154:157], v[56:59], v[150:153]
	ds_read_b128 v[154:157], v205 offset:3072
	v_fmamk_f32 v223, v166, 0xbfb8aa3b, v247
	s_waitcnt lgkmcnt(1)
	v_mfma_f32_16x16x32_bf16 v[150:153], v[122:125], v[44:47], 0
	v_mfma_f32_16x16x32_bf16 v[122:125], v[122:125], v[60:63], 0
	s_nop 2
	v_fmamk_f32 v220, v165, 0xbfb8aa3b, v246
	v_fmamk_f32 v221, v164, 0xbfb8aa3b, v246
	v_fmamk_f32 v126, v163, 0xbfb8aa3b, v246
	s_waitcnt lgkmcnt(0)
	v_mfma_f32_16x16x32_bf16 v[150:153], v[154:157], v[48:51], v[150:153]
	v_fmamk_f32 v224, v162, 0xbfb8aa3b, v246
	v_mfma_f32_16x16x32_bf16 v[122:125], v[154:157], v[64:67], v[122:125]
	ds_read_b128 v[154:157], v207 offset:3072
	s_waitcnt lgkmcnt(0)
	v_mfma_f32_16x16x32_bf16 v[150:153], v[154:157], v[52:55], v[150:153]
	v_mfma_f32_16x16x32_bf16 v[122:125], v[154:157], v[68:71], v[122:125]
	ds_read_b128 v[154:157], v208 offset:3072
	s_waitcnt lgkmcnt(0)
	v_mfma_f32_16x16x32_bf16 v[150:153], v[154:157], v[56:59], v[150:153]
	s_nop 7
	v_fmamk_f32 v174, v153, 0xbfb8aa3b, v246
	v_mfma_f32_16x16x32_bf16 v[122:125], v[154:157], v[72:75], v[122:125]
	v_fmamk_f32 v175, v152, 0xbfb8aa3b, v246
	v_fmamk_f32 v218, v151, 0xbfb8aa3b, v246
	v_fmamk_f32 v150, v150, 0xbfb8aa3b, v246
	s_nop 4
	v_fmamk_f32 v1, v125, 0xbfb8aa3b, v247
	v_fmamk_f32 v154, v124, 0xbfb8aa3b, v247
	v_fmamk_f32 v156, v123, 0xbfb8aa3b, v247
	v_fmamk_f32 v219, v122, 0xbfb8aa3b, v247
	v_fmamk_f32 v122, v169, 0xbfb8aa3b, v247
	v_fmamk_f32 v124, v168, 0xbfb8aa3b, v247
	s_cbranch_vccnz .LBB0_967
; __device__ __forceinline__ float bf2f(unsigned b) { return __uint_as_float(b << 16); }
; __device__ __forceinline__ float fexp(float x) { return __builtin_amdgcn_exp2f(x * 1.4426950408889634f); }
; __device__ __forceinline__ float fsqrt(float x) { return __builtin_amdgcn_sqrtf(x); }
; __device__ __forceinline__ float sigmoidf_(float x) { return frcp(1.0f + fexp(-x)); }
; __device__ __forceinline__ int ukey(int tk) { return ((tk >> 4) << 2) | (tk & 3); }
; __device__ __forceinline__ void lru_scan_phase(const Params& p, int slot, const bf16_t* upre, bf16_t* hf, bf16_t* hb, char* smem, const bf16_t* gateA, bf16_t* gate_out) {
;     ...
;         } else {
; #pragma unroll
;     ...
;                 const int mt = ii >> 2, j = ii & 3, tk = fq * 16 + ii;
;                 const float uval = bf2f(*reinterpret_cast<const bf16_t*>(smem + tk * 256 + (((chw >> 3) ^ ukey(tk)) * 16) + (chw & 7) * 2));
;                 const float r = sigmoidf_(acc[0][mt][j] + gbr), iv = sigmoidf_(acc[1][mt][j] + gbi);
;                 const float av = fexp(-sp8 * r);
;                 const float bv = fsqrt(fmaxf(1.f - av * av, 0.f)) * iv * uval;
;                 acc[0][mt][j] = av; acc[1][mt][j] = bv;
;                 H = av * H + bv; P *= av;
;             }
;         }
	v_exp_f32_e32 v2, v174
	v_exp_f32_e32 v3, v1
	ds_read_u16 v110, v212 offset:3584
	ds_read_u16 v111, v211 offset:3840
	v_add_f32_e32 v2, 1.0, v2
	v_rcp_f32_e32 v2, v2
	v_add_f32_e32 v3, 1.0, v3
	v_rcp_f32_e32 v3, v3
	s_waitcnt lgkmcnt(0)
	v_lshlrev_b32_e32 v111, 16, v111
	v_mul_f32_e32 v2, v248, v2
	v_exp_f32_e32 v155, v2
	v_lshlrev_b32_e32 v110, 16, v110
	s_mov_b64 s[10:11], 0
	v_fma_f32 v2, -v155, v155, 1.0
	v_max_f32_e32 v2, 0, v2
	v_sqrt_f32_e32 v109, v2
	v_exp_f32_e32 v2, v175
	s_nop 0
	v_add_f32_e32 v2, 1.0, v2
	v_rcp_f32_e32 v108, v2
	v_exp_f32_e32 v2, v154
	v_mul_f32_e32 v108, v248, v108
	v_exp_f32_e32 v157, v108
	v_add_f32_e32 v2, 1.0, v2
	v_rcp_f32_e32 v2, v2
	v_fma_f32 v108, -v157, v157, 1.0
	v_max_f32_e32 v108, 0, v108
	v_sqrt_f32_e32 v108, v108
	s_nop 0
	v_pk_mul_f32 v[2:3], v[2:3], v[108:109]
	s_nop 0
	v_pk_mul_f32 v[158:159], v[2:3], v[110:111]
	v_exp_f32_e32 v3, v218
	v_fma_f32 v2, 0, v155, v159
	v_mov_b32_e32 v112, v158
	v_fmac_f32_e32 v112, v157, v2
	v_add_f32_e32 v3, 1.0, v3
	v_rcp_f32_e32 v108, v3
	v_mul_f32_e32 v2, v155, v157
	v_exp_f32_e32 v3, v156
	v_mul_f32_e32 v108, v248, v108
	v_exp_f32_e32 v151, v108
	v_add_f32_e32 v3, 1.0, v3
	ds_read_u16 v110, v209 offset:3072
	ds_read_u16 v111, v213 offset:3328
	v_rcp_f32_e32 v3, v3
	v_mul_f32_e32 v113, v151, v2
	v_exp_f32_e32 v2, v150
	v_fma_f32 v108, -v151, v151, 1.0
	v_max_f32_e32 v108, 0, v108
	v_sqrt_f32_e32 v109, v108
	v_add_f32_e32 v2, 1.0, v2
	v_rcp_f32_e32 v108, v2
	v_exp_f32_e32 v2, v219
	s_waitcnt lgkmcnt(0)
	v_lshlrev_b32_e32 v111, 16, v111
	v_mul_f32_e32 v108, v248, v108
	v_exp_f32_e32 v123, v108
	v_add_f32_e32 v2, 1.0, v2
	v_rcp_f32_e32 v2, v2
	v_lshlrev_b32_e32 v110, 16, v110
	v_fma_f32 v108, -v123, v123, 1.0
	v_max_f32_e32 v108, 0, v108
	v_sqrt_f32_e32 v108, v108
	s_nop 0
	v_pk_mul_f32 v[2:3], v[2:3], v[108:109]
	s_nop 0
	v_pk_mul_f32 v[128:129], v[2:3], v[110:111]
	v_exp_f32_e32 v3, v220
	v_fma_f32 v2, v151, v112, v129
	v_mov_b32_e32 v112, v128
	v_fmac_f32_e32 v112, v123, v2
	v_add_f32_e32 v3, 1.0, v3
	v_rcp_f32_e32 v108, v3
	v_mul_f32_e32 v2, v123, v113
	v_exp_f32_e32 v3, v122
	v_mul_f32_e32 v108, v248, v108
	v_exp_f32_e32 v125, v108
	v_add_f32_e32 v3, 1.0, v3
	ds_read_u16 v110, v212 offset:2560
	ds_read_u16 v111, v211 offset:2816
	v_rcp_f32_e32 v3, v3
	v_mul_f32_e32 v113, v125, v2
	v_exp_f32_e32 v2, v221
	v_fma_f32 v108, -v125, v125, 1.0
	v_max_f32_e32 v108, 0, v108
	v_sqrt_f32_e32 v109, v108
	v_add_f32_e32 v2, 1.0, v2
	v_rcp_f32_e32 v108, v2
	v_exp_f32_e32 v2, v124
	s_waitcnt lgkmcnt(0)
	v_lshlrev_b32_e32 v111, 16, v111
	v_mul_f32_e32 v108, v248, v108
	v_exp_f32_e32 v127, v108
	v_add_f32_e32 v2, 1.0, v2
	v_rcp_f32_e32 v2, v2
	v_lshlrev_b32_e32 v110, 16, v110
	v_fma_f32 v108, -v127, v127, 1.0
	v_max_f32_e32 v108, 0, v108
	v_sqrt_f32_e32 v108, v108
	s_nop 0
	v_pk_mul_f32 v[2:3], v[2:3], v[108:109]
	s_nop 0
	v_pk_mul_f32 v[160:161], v[2:3], v[110:111]
	v_exp_f32_e32 v3, v126
	v_fma_f32 v2, v125, v112, v161
	v_mov_b32_e32 v112, v160
	v_fmac_f32_e32 v112, v127, v2
	v_add_f32_e32 v3, 1.0, v3
	v_rcp_f32_e32 v108, v3
	v_mul_f32_e32 v2, v127, v113
	v_exp_f32_e32 v3, v222
	v_mul_f32_e32 v108, v248, v108
	v_exp_f32_e32 v216, v108
	v_add_f32_e32 v3, 1.0, v3
	ds_read_u16 v110, v209 offset:2048
	ds_read_u16 v111, v213 offset:2304
	v_rcp_f32_e32 v3, v3
	v_mul_f32_e32 v113, v216, v2
	v_exp_f32_e32 v2, v224
	v_fma_f32 v108, -v216, v216, 1.0
	v_max_f32_e32 v108, 0, v108
	v_sqrt_f32_e32 v109, v108
	v_add_f32_e32 v2, 1.0, v2
	v_rcp_f32_e32 v108, v2
	v_exp_f32_e32 v2, v223
	s_waitcnt lgkmcnt(0)
	v_lshlrev_b32_e32 v111, 16, v111
	v_mul_f32_e32 v108, v248, v108
	v_exp_f32_e32 v217, v108
	v_add_f32_e32 v2, 1.0, v2
	v_rcp_f32_e32 v2, v2
	v_lshlrev_b32_e32 v110, 16, v110
	v_fma_f32 v108, -v217, v217, 1.0
	v_max_f32_e32 v108, 0, v108
	v_sqrt_f32_e32 v108, v108
	s_nop 0
	v_pk_mul_f32 v[2:3], v[2:3], v[108:109]
	s_nop 0
	v_pk_mul_f32 v[162:163], v[2:3], v[110:111]
	v_exp_f32_e32 v3, v226
	v_fma_f32 v2, v216, v112, v163
	v_mov_b32_e32 v112, v162
	v_fmac_f32_e32 v112, v217, v2
	v_add_f32_e32 v3, 1.0, v3
	v_rcp_f32_e32 v108, v3
	v_mul_f32_e32 v2, v217, v113
	v_exp_f32_e32 v3, v225
	v_mul_f32_e32 v108, v248, v108
	v_exp_f32_e32 v214, v108
	v_add_f32_e32 v3, 1.0, v3
	ds_read_u16 v110, v212 offset:1536
	ds_read_u16 v111, v211 offset:1792
	v_rcp_f32_e32 v3, v3
	v_mul_f32_e32 v113, v214, v2
	v_exp_f32_e32 v2, v227
	v_fma_f32 v108, -v214, v214, 1.0
	v_max_f32_e32 v108, 0, v108
	v_sqrt_f32_e32 v109, v108
	v_add_f32_e32 v2, 1.0, v2
	v_rcp_f32_e32 v108, v2
	v_exp_f32_e32 v2, v228
	s_waitcnt lgkmcnt(0)
	v_lshlrev_b32_e32 v111, 16, v111
	v_mul_f32_e32 v108, v248, v108
	v_exp_f32_e32 v215, v108
	v_add_f32_e32 v2, 1.0, v2
	v_rcp_f32_e32 v2, v2
	v_lshlrev_b32_e32 v110, 16, v110
	v_fma_f32 v108, -v215, v215, 1.0
	v_max_f32_e32 v108, 0, v108
	v_sqrt_f32_e32 v108, v108
	s_nop 0
	v_pk_mul_f32 v[2:3], v[2:3], v[108:109]
	s_nop 0
	v_pk_mul_f32 v[132:133], v[2:3], v[110:111]
	v_fma_f32 v2, v214, v112, v133
	v_mov_b32_e32 v3, v132
	v_fmac_f32_e32 v3, v215, v2
	ds_read_u16 v2, v213 offset:1280
	v_exp_f32_e32 v109, v229
	v_mul_f32_e32 v108, v215, v113
	s_waitcnt lgkmcnt(0)
	v_lshlrev_b32_e32 v110, 16, v2
	v_exp_f32_e32 v2, v230
	v_add_f32_e32 v109, 1.0, v109
	v_rcp_f32_e32 v109, v109
	v_add_f32_e32 v2, 1.0, v2
	v_rcp_f32_e32 v2, v2
	s_nop 0
	v_mul_f32_e32 v2, v248, v2
	v_exp_f32_e32 v111, v2
	s_nop 0
	v_fma_f32 v2, -v111, v111, 1.0
	v_max_f32_e32 v2, 0, v2
	v_sqrt_f32_e32 v2, v2
	s_nop 0
	v_mul_f32_e32 v2, v109, v2
	v_pk_mul_f32 v[168:169], v[2:3], v[110:111]
	s_nop 0
	v_pk_fma_f32 v[2:3], v[2:3], v[110:111], v[168:169] op_sel_hi:[1,1,0]
	ds_read_u16 v2, v209 offset:1024
	v_mul_f32_e32 v110, v111, v108
	v_exp_f32_e32 v108, v231
	s_waitcnt lgkmcnt(0)
; __device__ __forceinline__ float bf2f(unsigned b) { return __uint_as_float(b << 16); }
; __device__ __forceinline__ float fexp(float x) { return __builtin_amdgcn_exp2f(x * 1.4426950408889634f); }
; __device__ __forceinline__ float fsqrt(float x) { return __builtin_amdgcn_sqrtf(x); }
; __device__ __forceinline__ float sigmoidf_(float x) { return frcp(1.0f + fexp(-x)); }
; __device__ __forceinline__ int ukey(int tk) { return ((tk >> 4) << 2) | (tk & 3); }
; __device__ __forceinline__ void lru_scan_phase(const Params& p, int slot, const bf16_t* upre, bf16_t* hf, bf16_t* hb, char* smem, const bf16_t* gateA, bf16_t* gate_out) {
;     ...
;         if (d == 0) {
; #pragma unroll
;             for (int ii = 0; ii < 16; ++ii) {
;                 const int mt = ii >> 2, j = ii & 3, tk = fq * 16 + ii;
;                 const float uval = bf2f(*reinterpret_cast<const bf16_t*>(smem + tk * 256 + (((chw >> 3) ^ ukey(tk)) * 16) + (chw & 7) * 2));
;                 const float r = sigmoidf_(acc[0][mt][j] + gbr), iv = sigmoidf_(acc[1][mt][j] + gbi);
;                 const float av = fexp(-sp8 * r);
;                 const float bv = fsqrt(fmaxf(1.f - av * av, 0.f)) * iv * uval;
;                 acc[0][mt][j] = av; acc[1][mt][j] = bv;
;                 H = av * H + bv; P *= av;
;             }
;         } else {
; #pragma unroll
;     ...
;                 const int mt = ii >> 2, j = ii & 3, tk = fq * 16 + ii;
;                 const float uval = bf2f(*reinterpret_cast<const bf16_t*>(smem + tk * 256 + (((chw >> 3) ^ ukey(tk)) * 16) + (chw & 7) * 2));
;                 const float r = sigmoidf_(acc[0][mt][j] + gbr), iv = sigmoidf_(acc[1][mt][j] + gbi);
;                 const float av = fexp(-sp8 * r);
;                 const float bv = fsqrt(fmaxf(1.f - av * av, 0.f)) * iv * uval;
;                 acc[0][mt][j] = av; acc[1][mt][j] = bv;
;                 H = av * H + bv; P *= av;
;             }
;         }
	v_lshlrev_b32_e32 v112, 16, v2
	v_exp_f32_e32 v2, v232
	v_add_f32_e32 v108, 1.0, v108
	v_rcp_f32_e32 v108, v108
	v_add_f32_e32 v2, 1.0, v2
	v_rcp_f32_e32 v2, v2
	s_nop 0
	v_mul_f32_e32 v2, v248, v2
	v_exp_f32_e32 v113, v2
	s_nop 0
	v_fma_f32 v2, -v113, v113, 1.0
	v_max_f32_e32 v2, 0, v2
	v_sqrt_f32_e32 v2, v2
	v_mul_f32_e32 v110, v113, v110
	v_mul_f32_e32 v2, v108, v2
	v_pk_mul_f32 v[130:131], v[2:3], v[112:113]
	s_nop 0
	v_pk_fma_f32 v[108:109], v[2:3], v[112:113], v[130:131] op_sel_hi:[1,1,0]
	v_exp_f32_e32 v3, v233
	v_exp_f32_e32 v108, v234
	ds_read_u16 v2, v211 offset:768
	v_add_f32_e32 v3, 1.0, v3
	v_rcp_f32_e32 v3, v3
	v_add_f32_e32 v108, 1.0, v108
	v_rcp_f32_e32 v108, v108
	s_waitcnt lgkmcnt(0)
	v_lshlrev_b32_e32 v2, 16, v2
	v_mul_f32_e32 v3, v248, v3
	v_exp_f32_e32 v3, v3
	s_nop 0
	v_fma_f32 v112, -v3, v3, 1.0
	v_max_f32_e32 v112, 0, v112
	v_sqrt_f32_e32 v112, v112
	s_nop 0
	v_mul_f32_e32 v108, v108, v112
	v_pk_mul_f32 v[170:171], v[108:109], v[2:3]
	s_nop 0
	v_pk_fma_f32 v[152:153], v[108:109], v[2:3], v[170:171] op_sel_hi:[1,1,0]
	v_exp_f32_e32 v109, v236
	v_mul_f32_e32 v2, v3, v110
	v_exp_f32_e32 v110, v235
	v_add_f32_e32 v109, 1.0, v109
	v_rcp_f32_e32 v109, v109
	ds_read_u16 v108, v212 offset:512
	v_add_f32_e32 v110, 1.0, v110
	v_rcp_f32_e32 v110, v110
	v_mul_f32_e32 v109, v248, v109
	v_exp_f32_e32 v109, v109
	s_waitcnt lgkmcnt(0)
	v_lshlrev_b32_e32 v108, 16, v108
	v_fma_f32 v112, -v109, v109, 1.0
	v_max_f32_e32 v112, 0, v112
	v_sqrt_f32_e32 v112, v112
	v_mul_f32_e32 v2, v109, v2
	v_mul_f32_e32 v152, v110, v112
	v_pk_mul_f32 v[114:115], v[152:153], v[108:109]
	v_pk_fma_f32 v[164:165], v[152:153], v[108:109], v[114:115] op_sel_hi:[1,1,0]
	ds_read_u16 v108, v213 offset:256
	v_exp_f32_e32 v110, v237
	s_waitcnt lgkmcnt(0)
	v_lshlrev_b32_e32 v152, 16, v108
	v_exp_f32_e32 v108, v238
	v_add_f32_e32 v110, 1.0, v110
	v_rcp_f32_e32 v110, v110
	v_add_f32_e32 v108, 1.0, v108
	v_rcp_f32_e32 v108, v108
	s_nop 0
	v_mul_f32_e32 v108, v248, v108
	v_exp_f32_e32 v153, v108
	s_nop 0
	v_fma_f32 v108, -v153, v153, 1.0
	v_max_f32_e32 v108, 0, v108
	v_sqrt_f32_e32 v108, v108
	v_mul_f32_e32 v2, v153, v2
	v_mul_f32_e32 v164, v110, v108
	ds_read_u16 v108, v209
	v_pk_mul_f32 v[172:173], v[164:165], v[152:153]
	v_pk_fma_f32 v[166:167], v[164:165], v[152:153], v[172:173] op_sel_hi:[1,1,0]
	v_exp_f32_e32 v110, v239
	s_waitcnt lgkmcnt(0)
	v_lshlrev_b32_e32 v164, 16, v108
	v_exp_f32_e32 v108, v240
	v_add_f32_e32 v110, 1.0, v110
	v_rcp_f32_e32 v110, v110
	v_add_f32_e32 v108, 1.0, v108
	v_rcp_f32_e32 v108, v108
	s_nop 0
	v_mul_f32_e32 v108, v248, v108
	v_exp_f32_e32 v165, v108
	s_nop 0
	v_fma_f32 v108, -v165, v165, 1.0
	v_max_f32_e32 v108, 0, v108
	v_sqrt_f32_e32 v108, v108
	s_nop 0
	v_mul_f32_e32 v166, v110, v108
	v_pk_mul_f32 v[166:167], v[166:167], v[164:165]
	v_mul_f32_e32 v108, v165, v2
	v_add_f32_e32 v110, v166, v167
.LBB0_967:
	s_andn2_b64 vcc, exec, s[10:11]
	s_mov_b32 s4, 3
	s_cbranch_vccnz .LBB0_969
	v_exp_f32_e32 v2, v240
	ds_read_u16 v110, v210
	ds_read_u16 v111, v213 offset:256
	ds_read_u16 v114, v212 offset:512
	ds_read_u16 v115, v211 offset:768
	v_add_f32_e32 v2, 1.0, v2
	v_rcp_f32_e32 v3, v2
	v_exp_f32_e32 v2, v239
	s_waitcnt lgkmcnt(2)
	v_lshlrev_b32_e32 v111, 16, v111
	v_mul_f32_e32 v3, v248, v3
	v_exp_f32_e32 v165, v3
	v_add_f32_e32 v2, 1.0, v2
	v_rcp_f32_e32 v2, v2
	v_lshlrev_b32_e32 v110, 16, v110
	v_fma_f32 v3, -v165, v165, 1.0
	v_max_f32_e32 v3, 0, v3
	v_sqrt_f32_e32 v108, v3
	v_exp_f32_e32 v3, v238
	s_waitcnt lgkmcnt(0)
	v_lshlrev_b32_e32 v115, 16, v115
	v_lshlrev_b32_e32 v114, 16, v114
	v_exp_f32_e32 v1, v1
	v_add_f32_e32 v3, 1.0, v3
	v_rcp_f32_e32 v109, v3
	v_exp_f32_e32 v3, v237
	v_add_f32_e32 v1, 1.0, v1
	v_mul_f32_e32 v109, v248, v109
	v_exp_f32_e32 v153, v109
	v_add_f32_e32 v3, 1.0, v3
	v_rcp_f32_e32 v3, v3
	v_rcp_f32_e32 v1, v1
	v_fma_f32 v109, -v153, v153, 1.0
	v_max_f32_e32 v109, 0, v109
	v_sqrt_f32_e32 v109, v109
	s_mov_b32 s4, 0
	v_pk_mul_f32 v[2:3], v[2:3], v[108:109]
	s_nop 0
	v_pk_mul_f32 v[166:167], v[2:3], v[110:111]
	v_exp_f32_e32 v3, v236
	v_exp_f32_e32 v109, v235
	v_add_f32_e32 v3, 1.0, v3
	v_rcp_f32_e32 v3, v3
	v_add_f32_e32 v109, 1.0, v109
	v_rcp_f32_e32 v110, v109
	v_exp_f32_e32 v111, v234
	v_mul_f32_e32 v3, v248, v3
	v_exp_f32_e32 v109, v3
	v_add_f32_e32 v111, 1.0, v111
	v_rcp_f32_e32 v111, v111
	v_fma_f32 v2, 0, v165, v166
	v_fma_f32 v3, -v109, v109, 1.0
	v_max_f32_e32 v3, 0, v3
	v_sqrt_f32_e32 v112, v3
	v_exp_f32_e32 v3, v233
	v_mov_b32_e32 v108, v167
	v_fmac_f32_e32 v108, v153, v2
	v_mul_f32_e32 v2, v165, v153
	v_add_f32_e32 v3, 1.0, v3
	v_rcp_f32_e32 v3, v3
	v_mul_f32_e32 v2, v109, v2
	v_mul_f32_e32 v3, v248, v3
	v_exp_f32_e32 v3, v3
	s_nop 0
	v_fma_f32 v113, -v3, v3, 1.0
	v_max_f32_e32 v113, 0, v113
	v_sqrt_f32_e32 v113, v113
	v_mul_f32_e32 v2, v3, v2
	v_pk_mul_f32 v[110:111], v[110:111], v[112:113]
	s_nop 0
	v_pk_mul_f32 v[114:115], v[110:111], v[114:115]
	v_fma_f32 v108, v109, v108, v114
	v_mov_b32_e32 v110, v115
	v_fmac_f32_e32 v110, v3, v108
	v_exp_f32_e32 v108, v232
	v_exp_f32_e32 v111, v231
	v_add_f32_e32 v108, 1.0, v108
	v_rcp_f32_e32 v108, v108
	v_add_f32_e32 v111, 1.0, v111
	v_rcp_f32_e32 v128, v111
	v_mul_f32_e32 v108, v248, v108
	v_exp_f32_e32 v113, v108
	v_exp_f32_e32 v111, v229
	v_fma_f32 v108, -v113, v113, 1.0
	v_max_f32_e32 v108, 0, v108
	v_sqrt_f32_e32 v130, v108
	v_exp_f32_e32 v108, v230
	v_add_f32_e32 v111, 1.0, v111
	v_rcp_f32_e32 v129, v111
	v_mul_f32_e32 v2, v2, v113
	v_add_f32_e32 v108, 1.0, v108
	v_rcp_f32_e32 v108, v108
	s_nop 0
	v_mul_f32_e32 v108, v248, v108
	v_exp_f32_e32 v111, v108
	s_nop 0
	v_fma_f32 v108, -v111, v111, 1.0
	v_max_f32_e32 v108, 0, v108
	v_sqrt_f32_e32 v131, v108
	ds_read_u16 v108, v210 offset:1024
	ds_read_u16 v112, v213 offset:1280
	v_mul_f32_e32 v2, v111, v2
	v_pk_mul_f32 v[128:129], v[128:129], v[130:131]
	s_waitcnt lgkmcnt(1)
; __device__ __forceinline__ float bf2f(unsigned b) { return __uint_as_float(b << 16); }
; __device__ __forceinline__ float fexp(float x) { return __builtin_amdgcn_exp2f(x * 1.4426950408889634f); }
; __device__ __forceinline__ float fsqrt(float x) { return __builtin_amdgcn_sqrtf(x); }
; __device__ __forceinline__ float sigmoidf_(float x) { return frcp(1.0f + fexp(-x)); }
; __device__ __forceinline__ int ukey(int tk) { return ((tk >> 4) << 2) | (tk & 3); }
; __device__ __forceinline__ void lru_scan_phase(const Params& p, int slot, const bf16_t* upre, bf16_t* hf, bf16_t* hb, char* smem, const bf16_t* gateA, bf16_t* gate_out) {
;     ...
;         if (d == 0) {
; #pragma unroll
;             for (int ii = 0; ii < 16; ++ii) {
;                 const int mt = ii >> 2, j = ii & 3, tk = fq * 16 + ii;
;                 const float uval = bf2f(*reinterpret_cast<const bf16_t*>(smem + tk * 256 + (((chw >> 3) ^ ukey(tk)) * 16) + (chw & 7) * 2));
;                 const float r = sigmoidf_(acc[0][mt][j] + gbr), iv = sigmoidf_(acc[1][mt][j] + gbi);
;                 const float av = fexp(-sp8 * r);
;                 const float bv = fsqrt(fmaxf(1.f - av * av, 0.f)) * iv * uval;
;                 acc[0][mt][j] = av; acc[1][mt][j] = bv;
;                 H = av * H + bv; P *= av;
;             }
	v_lshlrev_b32_e32 v132, 16, v108
	s_waitcnt lgkmcnt(0)
	v_lshlrev_b32_e32 v133, 16, v112
	v_pk_mul_f32 v[130:131], v[128:129], v[132:133]
	v_fma_f32 v108, v113, v110, v130
	v_mov_b32_e32 v110, v131
	v_fmac_f32_e32 v110, v111, v108
	v_exp_f32_e32 v108, v227
	v_exp_f32_e32 v112, v228
	v_add_f32_e32 v108, 1.0, v108
	v_rcp_f32_e32 v108, v108
	v_add_f32_e32 v112, 1.0, v112
	v_rcp_f32_e32 v128, v112
	v_mul_f32_e32 v108, v248, v108
	v_exp_f32_e32 v215, v108
	v_exp_f32_e32 v112, v225
	v_fma_f32 v108, -v215, v215, 1.0
	v_max_f32_e32 v108, 0, v108
	v_sqrt_f32_e32 v132, v108
	v_exp_f32_e32 v108, v226
	v_add_f32_e32 v112, 1.0, v112
	v_rcp_f32_e32 v129, v112
	v_mul_f32_e32 v2, v215, v2
	v_add_f32_e32 v108, 1.0, v108
	v_rcp_f32_e32 v108, v108
	s_nop 0
	v_mul_f32_e32 v108, v248, v108
	v_exp_f32_e32 v214, v108
	s_nop 0
	v_fma_f32 v108, -v214, v214, 1.0
	v_max_f32_e32 v108, 0, v108
	v_sqrt_f32_e32 v133, v108
	ds_read_u16 v108, v212 offset:1536
	ds_read_u16 v112, v211 offset:1792
	v_mul_f32_e32 v2, v214, v2
	v_pk_mul_f32 v[128:129], v[128:129], v[132:133]
	s_waitcnt lgkmcnt(1)
	v_lshlrev_b32_e32 v158, 16, v108
	s_waitcnt lgkmcnt(0)
	v_lshlrev_b32_e32 v159, 16, v112
	v_pk_mul_f32 v[132:133], v[128:129], v[158:159]
	v_fma_f32 v108, v215, v110, v132
	v_mov_b32_e32 v110, v133
	v_fmac_f32_e32 v110, v214, v108
	v_exp_f32_e32 v108, v224
	v_exp_f32_e32 v112, v223
	v_add_f32_e32 v108, 1.0, v108
	v_rcp_f32_e32 v108, v108
	v_add_f32_e32 v112, 1.0, v112
	v_rcp_f32_e32 v128, v112
	v_mul_f32_e32 v108, v248, v108
	v_exp_f32_e32 v217, v108
	v_exp_f32_e32 v112, v222
	v_fma_f32 v108, -v217, v217, 1.0
	v_max_f32_e32 v108, 0, v108
	v_sqrt_f32_e32 v158, v108
	v_exp_f32_e32 v108, v126
	v_add_f32_e32 v112, 1.0, v112
	v_rcp_f32_e32 v129, v112
	v_mul_f32_e32 v2, v2, v217
	v_add_f32_e32 v108, 1.0, v108
	v_rcp_f32_e32 v108, v108
	s_nop 0
	v_mul_f32_e32 v108, v248, v108
	v_exp_f32_e32 v216, v108
	s_nop 0
	v_fma_f32 v108, -v216, v216, 1.0
	v_max_f32_e32 v108, 0, v108
	v_sqrt_f32_e32 v159, v108
	ds_read_u16 v108, v210 offset:2048
	ds_read_u16 v112, v213 offset:2304
	v_mul_f32_e32 v2, v216, v2
	v_pk_mul_f32 v[128:129], v[128:129], v[158:159]
	s_waitcnt lgkmcnt(1)
	v_lshlrev_b32_e32 v126, 16, v108
	s_waitcnt lgkmcnt(0)
	v_lshlrev_b32_e32 v127, 16, v112
	v_pk_mul_f32 v[162:163], v[128:129], v[126:127]
	s_nop 0
	v_fma_f32 v108, v217, v110, v162
	v_mov_b32_e32 v125, v163
	v_fmac_f32_e32 v125, v216, v108
	ds_read_u16 v108, v212 offset:2560
	v_exp_f32_e32 v110, v124
	s_waitcnt lgkmcnt(0)
	v_lshlrev_b32_e32 v126, 16, v108
	v_exp_f32_e32 v108, v221
	v_add_f32_e32 v110, 1.0, v110
	v_rcp_f32_e32 v110, v110
	v_add_f32_e32 v108, 1.0, v108
	v_rcp_f32_e32 v108, v108
	s_nop 0
	v_mul_f32_e32 v108, v248, v108
	v_exp_f32_e32 v127, v108
	s_nop 0
	v_fma_f32 v108, -v127, v127, 1.0
	v_max_f32_e32 v108, 0, v108
	v_sqrt_f32_e32 v108, v108
	v_mul_f32_e32 v2, v127, v2
	v_mul_f32_e32 v124, v110, v108
	ds_read_u16 v108, v211 offset:2816
	v_pk_mul_f32 v[160:161], v[124:125], v[126:127]
	v_pk_fma_f32 v[128:129], v[124:125], v[126:127], v[160:161] op_sel_hi:[1,1,0]
	v_exp_f32_e32 v110, v122
	s_waitcnt lgkmcnt(0)
	v_lshlrev_b32_e32 v124, 16, v108
	v_exp_f32_e32 v108, v220
	v_add_f32_e32 v110, 1.0, v110
	v_rcp_f32_e32 v110, v110
	v_add_f32_e32 v108, 1.0, v108
	v_rcp_f32_e32 v108, v108
	s_nop 0
	v_mul_f32_e32 v108, v248, v108
	v_exp_f32_e32 v125, v108
	s_nop 0
	v_fma_f32 v108, -v125, v125, 1.0
	v_max_f32_e32 v108, 0, v108
	v_sqrt_f32_e32 v108, v108
	v_mul_f32_e32 v2, v125, v2
	v_mul_f32_e32 v128, v110, v108
	ds_read_u16 v108, v210 offset:3072
	v_exp_f32_e32 v110, v219
	v_pk_mul_f32 v[168:169], v[128:129], v[124:125]
	s_waitcnt lgkmcnt(0)
	v_lshlrev_b32_e32 v122, 16, v108
	v_exp_f32_e32 v108, v150
	v_add_f32_e32 v110, 1.0, v110
	v_rcp_f32_e32 v110, v110
	v_pk_fma_f32 v[158:159], v[128:129], v[124:125], v[168:169] op_sel_hi:[1,1,0]
	v_add_f32_e32 v108, 1.0, v108
	v_rcp_f32_e32 v108, v108
	v_mov_b32_e32 v161, v168
	v_mov_b32_e32 v168, v131
	v_mul_f32_e32 v108, v248, v108
	v_exp_f32_e32 v123, v108
	s_nop 0
	v_fma_f32 v108, -v123, v123, 1.0
	v_max_f32_e32 v108, 0, v108
	v_sqrt_f32_e32 v108, v108
	v_mul_f32_e32 v2, v2, v123
	v_mul_f32_e32 v158, v110, v108
	ds_read_u16 v108, v213 offset:3328
	v_exp_f32_e32 v110, v156
	v_pk_mul_f32 v[128:129], v[158:159], v[122:123]
	s_waitcnt lgkmcnt(0)
	v_lshlrev_b32_e32 v150, 16, v108
	v_exp_f32_e32 v108, v218
	v_add_f32_e32 v110, 1.0, v110
	v_rcp_f32_e32 v110, v110
	v_pk_fma_f32 v[158:159], v[158:159], v[122:123], v[128:129] op_sel_hi:[1,1,0]
	v_add_f32_e32 v108, 1.0, v108
	v_rcp_f32_e32 v108, v108
	s_nop 0
	v_mul_f32_e32 v108, v248, v108
	v_exp_f32_e32 v151, v108
	s_nop 0
	v_fma_f32 v108, -v151, v151, 1.0
	v_max_f32_e32 v108, 0, v108
	v_sqrt_f32_e32 v108, v108
	v_mul_f32_e32 v2, v151, v2
	v_mul_f32_e32 v158, v110, v108
	ds_read_u16 v108, v212 offset:3584
	v_exp_f32_e32 v110, v154
	v_pk_mul_f32 v[170:171], v[158:159], v[150:151]
	s_waitcnt lgkmcnt(0)
	v_lshlrev_b32_e32 v156, 16, v108
	v_exp_f32_e32 v108, v175
	v_add_f32_e32 v110, 1.0, v110
	v_rcp_f32_e32 v110, v110
	v_pk_fma_f32 v[172:173], v[158:159], v[150:151], v[170:171] op_sel_hi:[1,1,0]
	v_add_f32_e32 v108, 1.0, v108
	v_rcp_f32_e32 v108, v108
	v_mov_b32_e32 v129, v170
	v_mov_b32_e32 v170, v115
	v_mul_f32_e32 v108, v248, v108
	v_exp_f32_e32 v157, v108
	s_nop 0
	v_fma_f32 v108, -v157, v157, 1.0
	v_max_f32_e32 v108, 0, v108
	v_sqrt_f32_e32 v108, v108
	v_mul_f32_e32 v2, v157, v2
	v_mul_f32_e32 v172, v110, v108
	ds_read_u16 v108, v211 offset:3840
	v_pk_mul_f32 v[158:159], v[172:173], v[156:157]
	s_waitcnt lgkmcnt(0)
	v_lshlrev_b32_e32 v154, 16, v108
	v_exp_f32_e32 v108, v174
	v_pk_fma_f32 v[172:173], v[172:173], v[156:157], v[158:159] op_sel_hi:[1,1,0]
	v_add_f32_e32 v108, 1.0, v108
	v_rcp_f32_e32 v108, v108
	s_nop 0
	v_mul_f32_e32 v108, v248, v108
	v_exp_f32_e32 v155, v108
	s_nop 0
	v_fma_f32 v108, -v155, v155, 1.0
	v_max_f32_e32 v108, 0, v108
	v_sqrt_f32_e32 v108, v108
	s_nop 0
	v_mul_f32_e32 v172, v1, v108
	v_pk_mul_f32 v[172:173], v[172:173], v[154:155]
	v_mul_f32_e32 v108, v155, v2
	v_add_f32_e32 v110, v172, v173
	v_mov_b32_e32 v159, v172
	v_mov_b32_e32 v172, v167
